# Swiglu fast-path epilogue stores without the nt hint (ACT stays L2-resident for FFN-down); on top of v24
# speedup vs baseline: 1.0150x; 1.0150x over previous
; __device__ __forceinline__ u32x4 pack8(const f32x4 a, const f32x4 b) { u32x4 w; w.x = cvt_pk_bf16(a[0], a[1]); w.y = cvt_pk_bf16(a[2], a[3]); w.z = cvt_pk_bf16(b[0], b[1]); w.w = cvt_pk_bf16(b[2], b[3]); return w; }
;     __device__ __forceinline__ void operator()(const f32x4 (&acc)[2][2][4][2], const Unit& u, int wr, int wc, int fr, int fq) const {
;     ...
;                 const int row = row0 + ai * 128 + m * 16; const float rs = (u.pm == pm0) ? RS[row & 255] : row_rstd(ss, row), rsl = -LOG2E_ * rs, rs2 = rs * rs;
;                 f32x4 t[2], q[2], e[2];
; #pragma unroll
;                 for (int n = 0; n < 2; ++n) { t[n] = acc[ai][0][m][n] * rsl; q[n] = acc[ai][0][m][n] * acc[ai][1][m][n]; }
; #pragma unroll
;                 for (int n = 0; n < 2; ++n)
; #pragma unroll
;                     for (int j = 0; j < 4; ++j) e[n][j] = __builtin_amdgcn_exp2f(t[n][j]);
; #pragma unroll
;                 for (int n = 0; n < 2; ++n) { e[n] = e[n] + 1.0f; q[n] = q[n] * rs2; }
; #pragma unroll
;                 for (int n = 0; n < 2; ++n)
; #pragma unroll
;                     for (int j = 0; j < 4; ++j) e[n][j] = __builtin_amdgcn_rcpf(e[n][j]);
;                 __builtin_nontemporal_store(pack8(q[0] * e[0], q[1] * e[1]), (u32x4*)(O + (size_t)row * DFF + col0));
.LBB0_228:
	s_cmp_lg_u32 s20, s29
	s_cbranch_scc1 .Lsw_slow
	v_lshl_add_u32 v146, s20, 8, v148
	v_lshl_or_b32 v147, s4, 7, v151
	v_mul_u32_u24_e32 v146, 0x1600, v146
	v_lshl_add_u32 v146, v147, 1, v146
	s_waitcnt lgkmcnt(7)
	v_mul_f32_e32 v140, 0xbfb8aa3b, v224
	v_mul_f32_e32 v138, v224, v224
	v_pk_mul_f32 v[154:155], v[126:127], v[140:141] op_sel_hi:[1,0]
	v_pk_mul_f32 v[156:157], v[128:129], v[140:141] op_sel_hi:[1,0]
	v_pk_mul_f32 v[158:159], v[122:123], v[140:141] op_sel_hi:[1,0]
	v_pk_mul_f32 v[160:161], v[124:125], v[140:141] op_sel_hi:[1,0]
	v_exp_f32_e32 v154, v154
	v_exp_f32_e32 v155, v155
	v_exp_f32_e32 v156, v156
	v_exp_f32_e32 v157, v157
	v_exp_f32_e32 v158, v158
	v_exp_f32_e32 v159, v159
	v_exp_f32_e32 v160, v160
	v_exp_f32_e32 v161, v161
	v_pk_mul_f32 v[118:119], v[126:127], v[118:119]
	v_pk_mul_f32 v[120:121], v[128:129], v[120:121]
	v_pk_mul_f32 v[114:115], v[122:123], v[114:115]
	v_pk_mul_f32 v[116:117], v[124:125], v[116:117]
	v_pk_add_f32 v[154:155], v[154:155], 1.0 op_sel_hi:[1,0]
	v_pk_add_f32 v[156:157], v[156:157], 1.0 op_sel_hi:[1,0]
	v_pk_add_f32 v[158:159], v[158:159], 1.0 op_sel_hi:[1,0]
	v_pk_add_f32 v[160:161], v[160:161], 1.0 op_sel_hi:[1,0]
	v_pk_mul_f32 v[118:119], v[118:119], v[138:139] op_sel_hi:[1,0]
	v_pk_mul_f32 v[120:121], v[120:121], v[138:139] op_sel_hi:[1,0]
	v_pk_mul_f32 v[114:115], v[114:115], v[138:139] op_sel_hi:[1,0]
	v_pk_mul_f32 v[116:117], v[116:117], v[138:139] op_sel_hi:[1,0]
	v_rcp_f32_e32 v154, v154
	v_rcp_f32_e32 v155, v155
	v_rcp_f32_e32 v156, v156
	v_rcp_f32_e32 v157, v157
	v_rcp_f32_e32 v158, v158
	v_rcp_f32_e32 v159, v159
	v_rcp_f32_e32 v160, v160
	v_rcp_f32_e32 v161, v161
	v_pk_mul_f32 v[118:119], v[118:119], v[154:155]
	v_pk_mul_f32 v[120:121], v[120:121], v[156:157]
	v_pk_mul_f32 v[114:115], v[114:115], v[158:159]
	v_pk_mul_f32 v[116:117], v[116:117], v[160:161]
	v_cvt_pk_bf16_f32 v126, v118, v119
	v_cvt_pk_bf16_f32 v127, v120, v121
	v_cvt_pk_bf16_f32 v128, v114, v115
	v_cvt_pk_bf16_f32 v129, v116, v117
	global_store_dwordx4 v146, v[126:129], s[36:37]
	s_waitcnt lgkmcnt(6)
	v_mul_f32_e32 v140, 0xbfb8aa3b, v225
	v_mul_f32_e32 v138, v225, v225
	v_add_u32_e32 v147, 0x16000, v146
	v_pk_mul_f32 v[154:155], v[110:111], v[140:141] op_sel_hi:[1,0]
	v_pk_mul_f32 v[156:157], v[112:113], v[140:141] op_sel_hi:[1,0]
	v_pk_mul_f32 v[158:159], v[106:107], v[140:141] op_sel_hi:[1,0]
	v_pk_mul_f32 v[160:161], v[108:109], v[140:141] op_sel_hi:[1,0]
	v_exp_f32_e32 v154, v154
	v_exp_f32_e32 v155, v155
	v_exp_f32_e32 v156, v156
	v_exp_f32_e32 v157, v157
	v_exp_f32_e32 v158, v158
	v_exp_f32_e32 v159, v159
	v_exp_f32_e32 v160, v160
	v_exp_f32_e32 v161, v161
	v_pk_mul_f32 v[102:103], v[110:111], v[102:103]
	v_pk_mul_f32 v[104:105], v[112:113], v[104:105]
	v_pk_mul_f32 v[98:99], v[106:107], v[98:99]
	v_pk_mul_f32 v[100:101], v[108:109], v[100:101]
	v_pk_add_f32 v[154:155], v[154:155], 1.0 op_sel_hi:[1,0]
	v_pk_add_f32 v[156:157], v[156:157], 1.0 op_sel_hi:[1,0]
	v_pk_add_f32 v[158:159], v[158:159], 1.0 op_sel_hi:[1,0]
	v_pk_add_f32 v[160:161], v[160:161], 1.0 op_sel_hi:[1,0]
	v_pk_mul_f32 v[102:103], v[102:103], v[138:139] op_sel_hi:[1,0]
	v_pk_mul_f32 v[104:105], v[104:105], v[138:139] op_sel_hi:[1,0]
	v_pk_mul_f32 v[98:99], v[98:99], v[138:139] op_sel_hi:[1,0]
	v_pk_mul_f32 v[100:101], v[100:101], v[138:139] op_sel_hi:[1,0]
	v_rcp_f32_e32 v154, v154
	v_rcp_f32_e32 v155, v155
	v_rcp_f32_e32 v156, v156
	v_rcp_f32_e32 v157, v157
	v_rcp_f32_e32 v158, v158
	v_rcp_f32_e32 v159, v159
	v_rcp_f32_e32 v160, v160
	v_rcp_f32_e32 v161, v161
	v_pk_mul_f32 v[102:103], v[102:103], v[154:155]
	v_pk_mul_f32 v[104:105], v[104:105], v[156:157]
	v_pk_mul_f32 v[98:99], v[98:99], v[158:159]
	v_pk_mul_f32 v[100:101], v[100:101], v[160:161]
	v_cvt_pk_bf16_f32 v110, v102, v103
	v_cvt_pk_bf16_f32 v111, v104, v105
	v_cvt_pk_bf16_f32 v112, v98, v99
	v_cvt_pk_bf16_f32 v113, v100, v101
	global_store_dwordx4 v147, v[110:113], s[36:37]
	s_waitcnt lgkmcnt(5)
	v_mul_f32_e32 v140, 0xbfb8aa3b, v226
	v_mul_f32_e32 v138, v226, v226
	v_add_u32_e32 v147, 0x2c000, v146
	v_pk_mul_f32 v[154:155], v[94:95], v[140:141] op_sel_hi:[1,0]
	v_pk_mul_f32 v[156:157], v[96:97], v[140:141] op_sel_hi:[1,0]
	v_pk_mul_f32 v[158:159], v[90:91], v[140:141] op_sel_hi:[1,0]
	v_pk_mul_f32 v[160:161], v[92:93], v[140:141] op_sel_hi:[1,0]
	v_exp_f32_e32 v154, v154
	v_exp_f32_e32 v155, v155
	v_exp_f32_e32 v156, v156
	v_exp_f32_e32 v157, v157
	v_exp_f32_e32 v158, v158
	v_exp_f32_e32 v159, v159
	v_exp_f32_e32 v160, v160
	v_exp_f32_e32 v161, v161
	v_pk_mul_f32 v[86:87], v[94:95], v[86:87]
	v_pk_mul_f32 v[88:89], v[96:97], v[88:89]
	v_pk_mul_f32 v[82:83], v[90:91], v[82:83]
	v_pk_mul_f32 v[84:85], v[92:93], v[84:85]
	v_pk_add_f32 v[154:155], v[154:155], 1.0 op_sel_hi:[1,0]
	v_pk_add_f32 v[156:157], v[156:157], 1.0 op_sel_hi:[1,0]
	v_pk_add_f32 v[158:159], v[158:159], 1.0 op_sel_hi:[1,0]
	v_pk_add_f32 v[160:161], v[160:161], 1.0 op_sel_hi:[1,0]
	v_pk_mul_f32 v[86:87], v[86:87], v[138:139] op_sel_hi:[1,0]
	v_pk_mul_f32 v[88:89], v[88:89], v[138:139] op_sel_hi:[1,0]
	v_pk_mul_f32 v[82:83], v[82:83], v[138:139] op_sel_hi:[1,0]
	v_pk_mul_f32 v[84:85], v[84:85], v[138:139] op_sel_hi:[1,0]
	v_rcp_f32_e32 v154, v154
	v_rcp_f32_e32 v155, v155
	v_rcp_f32_e32 v156, v156
	v_rcp_f32_e32 v157, v157
	v_rcp_f32_e32 v158, v158
	v_rcp_f32_e32 v159, v159
	v_rcp_f32_e32 v160, v160
	v_rcp_f32_e32 v161, v161
	v_pk_mul_f32 v[86:87], v[86:87], v[154:155]
	v_pk_mul_f32 v[88:89], v[88:89], v[156:157]
	v_pk_mul_f32 v[82:83], v[82:83], v[158:159]
	v_pk_mul_f32 v[84:85], v[84:85], v[160:161]
	v_cvt_pk_bf16_f32 v94, v86, v87
	v_cvt_pk_bf16_f32 v95, v88, v89
	v_cvt_pk_bf16_f32 v96, v82, v83
	v_cvt_pk_bf16_f32 v97, v84, v85
	global_store_dwordx4 v147, v[94:97], s[36:37]
	s_waitcnt lgkmcnt(4)
; __device__ __forceinline__ u32x4 pack8(const f32x4 a, const f32x4 b) { u32x4 w; w.x = cvt_pk_bf16(a[0], a[1]); w.y = cvt_pk_bf16(a[2], a[3]); w.z = cvt_pk_bf16(b[0], b[1]); w.w = cvt_pk_bf16(b[2], b[3]); return w; }
;     __device__ __forceinline__ void operator()(const f32x4 (&acc)[2][2][4][2], const Unit& u, int wr, int wc, int fr, int fq) const {
;     ...
;                 const int row = row0 + ai * 128 + m * 16; const float rs = (u.pm == pm0) ? RS[row & 255] : row_rstd(ss, row), rsl = -LOG2E_ * rs, rs2 = rs * rs;
;                 f32x4 t[2], q[2], e[2];
; #pragma unroll
;                 for (int n = 0; n < 2; ++n) { t[n] = acc[ai][0][m][n] * rsl; q[n] = acc[ai][0][m][n] * acc[ai][1][m][n]; }
; #pragma unroll
;                 for (int n = 0; n < 2; ++n)
; #pragma unroll
;                     for (int j = 0; j < 4; ++j) e[n][j] = __builtin_amdgcn_exp2f(t[n][j]);
; #pragma unroll
;                 for (int n = 0; n < 2; ++n) { e[n] = e[n] + 1.0f; q[n] = q[n] * rs2; }
; #pragma unroll
;                 for (int n = 0; n < 2; ++n)
; #pragma unroll
;                     for (int j = 0; j < 4; ++j) e[n][j] = __builtin_amdgcn_rcpf(e[n][j]);
;                 __builtin_nontemporal_store(pack8(q[0] * e[0], q[1] * e[1]), (u32x4*)(O + (size_t)row * DFF + col0));
	v_mul_f32_e32 v140, 0xbfb8aa3b, v227
	v_mul_f32_e32 v138, v227, v227
	v_add_u32_e32 v147, 0x42000, v146
	v_pk_mul_f32 v[154:155], v[78:79], v[140:141] op_sel_hi:[1,0]
	v_pk_mul_f32 v[156:157], v[80:81], v[140:141] op_sel_hi:[1,0]
	v_pk_mul_f32 v[158:159], v[74:75], v[140:141] op_sel_hi:[1,0]
	v_pk_mul_f32 v[160:161], v[76:77], v[140:141] op_sel_hi:[1,0]
	v_exp_f32_e32 v154, v154
	v_exp_f32_e32 v155, v155
	v_exp_f32_e32 v156, v156
	v_exp_f32_e32 v157, v157
	v_exp_f32_e32 v158, v158
	v_exp_f32_e32 v159, v159
	v_exp_f32_e32 v160, v160
	v_exp_f32_e32 v161, v161
	v_pk_mul_f32 v[70:71], v[78:79], v[70:71]
	v_pk_mul_f32 v[72:73], v[80:81], v[72:73]
	v_pk_mul_f32 v[66:67], v[74:75], v[66:67]
	v_pk_mul_f32 v[68:69], v[76:77], v[68:69]
	v_pk_add_f32 v[154:155], v[154:155], 1.0 op_sel_hi:[1,0]
	v_pk_add_f32 v[156:157], v[156:157], 1.0 op_sel_hi:[1,0]
	v_pk_add_f32 v[158:159], v[158:159], 1.0 op_sel_hi:[1,0]
	v_pk_add_f32 v[160:161], v[160:161], 1.0 op_sel_hi:[1,0]
	v_pk_mul_f32 v[70:71], v[70:71], v[138:139] op_sel_hi:[1,0]
	v_pk_mul_f32 v[72:73], v[72:73], v[138:139] op_sel_hi:[1,0]
	v_pk_mul_f32 v[66:67], v[66:67], v[138:139] op_sel_hi:[1,0]
	v_pk_mul_f32 v[68:69], v[68:69], v[138:139] op_sel_hi:[1,0]
	v_rcp_f32_e32 v154, v154
	v_rcp_f32_e32 v155, v155
	v_rcp_f32_e32 v156, v156
	v_rcp_f32_e32 v157, v157
	v_rcp_f32_e32 v158, v158
	v_rcp_f32_e32 v159, v159
	v_rcp_f32_e32 v160, v160
	v_rcp_f32_e32 v161, v161
	v_pk_mul_f32 v[70:71], v[70:71], v[154:155]
	v_pk_mul_f32 v[72:73], v[72:73], v[156:157]
	v_pk_mul_f32 v[66:67], v[66:67], v[158:159]
	v_pk_mul_f32 v[68:69], v[68:69], v[160:161]
	v_cvt_pk_bf16_f32 v78, v70, v71
	v_cvt_pk_bf16_f32 v79, v72, v73
	v_cvt_pk_bf16_f32 v80, v66, v67
	v_cvt_pk_bf16_f32 v81, v68, v69
	global_store_dwordx4 v147, v[78:81], s[36:37]
	s_waitcnt lgkmcnt(3)
	v_mul_f32_e32 v140, 0xbfb8aa3b, v228
	v_mul_f32_e32 v138, v228, v228
	v_add_u32_e32 v147, 0xb0000, v146
	v_pk_mul_f32 v[154:155], v[62:63], v[140:141] op_sel_hi:[1,0]
	v_pk_mul_f32 v[156:157], v[64:65], v[140:141] op_sel_hi:[1,0]
	v_pk_mul_f32 v[158:159], v[58:59], v[140:141] op_sel_hi:[1,0]
	v_pk_mul_f32 v[160:161], v[60:61], v[140:141] op_sel_hi:[1,0]
	v_exp_f32_e32 v154, v154
	v_exp_f32_e32 v155, v155
	v_exp_f32_e32 v156, v156
	v_exp_f32_e32 v157, v157
	v_exp_f32_e32 v158, v158
	v_exp_f32_e32 v159, v159
	v_exp_f32_e32 v160, v160
	v_exp_f32_e32 v161, v161
	v_pk_mul_f32 v[54:55], v[62:63], v[54:55]
	v_pk_mul_f32 v[56:57], v[64:65], v[56:57]
	v_pk_mul_f32 v[50:51], v[58:59], v[50:51]
	v_pk_mul_f32 v[52:53], v[60:61], v[52:53]
	v_pk_add_f32 v[154:155], v[154:155], 1.0 op_sel_hi:[1,0]
	v_pk_add_f32 v[156:157], v[156:157], 1.0 op_sel_hi:[1,0]
	v_pk_add_f32 v[158:159], v[158:159], 1.0 op_sel_hi:[1,0]
	v_pk_add_f32 v[160:161], v[160:161], 1.0 op_sel_hi:[1,0]
	v_pk_mul_f32 v[54:55], v[54:55], v[138:139] op_sel_hi:[1,0]
	v_pk_mul_f32 v[56:57], v[56:57], v[138:139] op_sel_hi:[1,0]
	v_pk_mul_f32 v[50:51], v[50:51], v[138:139] op_sel_hi:[1,0]
	v_pk_mul_f32 v[52:53], v[52:53], v[138:139] op_sel_hi:[1,0]
	v_rcp_f32_e32 v154, v154
	v_rcp_f32_e32 v155, v155
	v_rcp_f32_e32 v156, v156
	v_rcp_f32_e32 v157, v157
	v_rcp_f32_e32 v158, v158
	v_rcp_f32_e32 v159, v159
	v_rcp_f32_e32 v160, v160
	v_rcp_f32_e32 v161, v161
	v_pk_mul_f32 v[54:55], v[54:55], v[154:155]
	v_pk_mul_f32 v[56:57], v[56:57], v[156:157]
	v_pk_mul_f32 v[50:51], v[50:51], v[158:159]
	v_pk_mul_f32 v[52:53], v[52:53], v[160:161]
	v_cvt_pk_bf16_f32 v62, v54, v55
	v_cvt_pk_bf16_f32 v63, v56, v57
	v_cvt_pk_bf16_f32 v64, v50, v51
	v_cvt_pk_bf16_f32 v65, v52, v53
	global_store_dwordx4 v147, v[62:65], s[36:37]
	s_waitcnt lgkmcnt(2)
	v_mul_f32_e32 v140, 0xbfb8aa3b, v229
	v_mul_f32_e32 v138, v229, v229
	v_add_u32_e32 v147, 0xc6000, v146
	v_pk_mul_f32 v[154:155], v[46:47], v[140:141] op_sel_hi:[1,0]
	v_pk_mul_f32 v[156:157], v[48:49], v[140:141] op_sel_hi:[1,0]
	v_pk_mul_f32 v[158:159], v[42:43], v[140:141] op_sel_hi:[1,0]
	v_pk_mul_f32 v[160:161], v[44:45], v[140:141] op_sel_hi:[1,0]
	v_exp_f32_e32 v154, v154
	v_exp_f32_e32 v155, v155
	v_exp_f32_e32 v156, v156
	v_exp_f32_e32 v157, v157
	v_exp_f32_e32 v158, v158
	v_exp_f32_e32 v159, v159
	v_exp_f32_e32 v160, v160
	v_exp_f32_e32 v161, v161
	v_pk_mul_f32 v[38:39], v[46:47], v[38:39]
	v_pk_mul_f32 v[40:41], v[48:49], v[40:41]
	v_pk_mul_f32 v[34:35], v[42:43], v[34:35]
	v_pk_mul_f32 v[36:37], v[44:45], v[36:37]
	v_pk_add_f32 v[154:155], v[154:155], 1.0 op_sel_hi:[1,0]
	v_pk_add_f32 v[156:157], v[156:157], 1.0 op_sel_hi:[1,0]
	v_pk_add_f32 v[158:159], v[158:159], 1.0 op_sel_hi:[1,0]
	v_pk_add_f32 v[160:161], v[160:161], 1.0 op_sel_hi:[1,0]
	v_pk_mul_f32 v[38:39], v[38:39], v[138:139] op_sel_hi:[1,0]
	v_pk_mul_f32 v[40:41], v[40:41], v[138:139] op_sel_hi:[1,0]
	v_pk_mul_f32 v[34:35], v[34:35], v[138:139] op_sel_hi:[1,0]
	v_pk_mul_f32 v[36:37], v[36:37], v[138:139] op_sel_hi:[1,0]
	v_rcp_f32_e32 v154, v154
	v_rcp_f32_e32 v155, v155
	v_rcp_f32_e32 v156, v156
	v_rcp_f32_e32 v157, v157
	v_rcp_f32_e32 v158, v158
	v_rcp_f32_e32 v159, v159
	v_rcp_f32_e32 v160, v160
	v_rcp_f32_e32 v161, v161
	v_pk_mul_f32 v[38:39], v[38:39], v[154:155]
	v_pk_mul_f32 v[40:41], v[40:41], v[156:157]
	v_pk_mul_f32 v[34:35], v[34:35], v[158:159]
	v_pk_mul_f32 v[36:37], v[36:37], v[160:161]
	v_cvt_pk_bf16_f32 v46, v38, v39
	v_cvt_pk_bf16_f32 v47, v40, v41
	v_cvt_pk_bf16_f32 v48, v34, v35
	v_cvt_pk_bf16_f32 v49, v36, v37
	global_store_dwordx4 v147, v[46:49], s[36:37]
	s_waitcnt lgkmcnt(1)
; __device__ __forceinline__ u32x4 pack8(const f32x4 a, const f32x4 b) { u32x4 w; w.x = cvt_pk_bf16(a[0], a[1]); w.y = cvt_pk_bf16(a[2], a[3]); w.z = cvt_pk_bf16(b[0], b[1]); w.w = cvt_pk_bf16(b[2], b[3]); return w; }
;     __device__ __forceinline__ void operator()(const f32x4 (&acc)[2][2][4][2], const Unit& u, int wr, int wc, int fr, int fq) const {
;     ...
;                 const int row = row0 + ai * 128 + m * 16; const float rs = (u.pm == pm0) ? RS[row & 255] : row_rstd(ss, row), rsl = -LOG2E_ * rs, rs2 = rs * rs;
;                 f32x4 t[2], q[2], e[2];
; #pragma unroll
;                 for (int n = 0; n < 2; ++n) { t[n] = acc[ai][0][m][n] * rsl; q[n] = acc[ai][0][m][n] * acc[ai][1][m][n]; }
; #pragma unroll
;                 for (int n = 0; n < 2; ++n)
; #pragma unroll
;                     for (int j = 0; j < 4; ++j) e[n][j] = __builtin_amdgcn_exp2f(t[n][j]);
; #pragma unroll
;                 for (int n = 0; n < 2; ++n) { e[n] = e[n] + 1.0f; q[n] = q[n] * rs2; }
; #pragma unroll
;                 for (int n = 0; n < 2; ++n)
; #pragma unroll
;                     for (int j = 0; j < 4; ++j) e[n][j] = __builtin_amdgcn_rcpf(e[n][j]);
;                 __builtin_nontemporal_store(pack8(q[0] * e[0], q[1] * e[1]), (u32x4*)(O + (size_t)row * DFF + col0));
	v_mul_f32_e32 v140, 0xbfb8aa3b, v230
	v_mul_f32_e32 v138, v230, v230
	v_add_u32_e32 v147, 0xdc000, v146
	v_pk_mul_f32 v[154:155], v[30:31], v[140:141] op_sel_hi:[1,0]
	v_pk_mul_f32 v[156:157], v[32:33], v[140:141] op_sel_hi:[1,0]
	v_pk_mul_f32 v[158:159], v[26:27], v[140:141] op_sel_hi:[1,0]
	v_pk_mul_f32 v[160:161], v[28:29], v[140:141] op_sel_hi:[1,0]
	v_exp_f32_e32 v154, v154
	v_exp_f32_e32 v155, v155
	v_exp_f32_e32 v156, v156
	v_exp_f32_e32 v157, v157
	v_exp_f32_e32 v158, v158
	v_exp_f32_e32 v159, v159
	v_exp_f32_e32 v160, v160
	v_exp_f32_e32 v161, v161
	v_pk_mul_f32 v[22:23], v[30:31], v[22:23]
	v_pk_mul_f32 v[24:25], v[32:33], v[24:25]
	v_pk_mul_f32 v[18:19], v[26:27], v[18:19]
	v_pk_mul_f32 v[20:21], v[28:29], v[20:21]
	v_pk_add_f32 v[154:155], v[154:155], 1.0 op_sel_hi:[1,0]
	v_pk_add_f32 v[156:157], v[156:157], 1.0 op_sel_hi:[1,0]
	v_pk_add_f32 v[158:159], v[158:159], 1.0 op_sel_hi:[1,0]
	v_pk_add_f32 v[160:161], v[160:161], 1.0 op_sel_hi:[1,0]
	v_pk_mul_f32 v[22:23], v[22:23], v[138:139] op_sel_hi:[1,0]
	v_pk_mul_f32 v[24:25], v[24:25], v[138:139] op_sel_hi:[1,0]
	v_pk_mul_f32 v[18:19], v[18:19], v[138:139] op_sel_hi:[1,0]
	v_pk_mul_f32 v[20:21], v[20:21], v[138:139] op_sel_hi:[1,0]
	v_rcp_f32_e32 v154, v154
	v_rcp_f32_e32 v155, v155
	v_rcp_f32_e32 v156, v156
	v_rcp_f32_e32 v157, v157
	v_rcp_f32_e32 v158, v158
	v_rcp_f32_e32 v159, v159
	v_rcp_f32_e32 v160, v160
	v_rcp_f32_e32 v161, v161
	v_pk_mul_f32 v[22:23], v[22:23], v[154:155]
	v_pk_mul_f32 v[24:25], v[24:25], v[156:157]
	v_pk_mul_f32 v[18:19], v[18:19], v[158:159]
	v_pk_mul_f32 v[20:21], v[20:21], v[160:161]
	v_cvt_pk_bf16_f32 v30, v22, v23
	v_cvt_pk_bf16_f32 v31, v24, v25
	v_cvt_pk_bf16_f32 v32, v18, v19
	v_cvt_pk_bf16_f32 v33, v20, v21
	global_store_dwordx4 v147, v[30:33], s[36:37]
	s_waitcnt lgkmcnt(0)
	v_mul_f32_e32 v140, 0xbfb8aa3b, v231
	v_mul_f32_e32 v138, v231, v231
	v_add_u32_e32 v147, 0xf2000, v146
	v_pk_mul_f32 v[154:155], v[14:15], v[140:141] op_sel_hi:[1,0]
	v_pk_mul_f32 v[156:157], v[16:17], v[140:141] op_sel_hi:[1,0]
	v_pk_mul_f32 v[158:159], v[10:11], v[140:141] op_sel_hi:[1,0]
	v_pk_mul_f32 v[160:161], v[12:13], v[140:141] op_sel_hi:[1,0]
	v_exp_f32_e32 v154, v154
	v_exp_f32_e32 v155, v155
	v_exp_f32_e32 v156, v156
	v_exp_f32_e32 v157, v157
	v_exp_f32_e32 v158, v158
	v_exp_f32_e32 v159, v159
	v_exp_f32_e32 v160, v160
	v_exp_f32_e32 v161, v161
	v_pk_mul_f32 v[6:7], v[14:15], v[6:7]
	v_pk_mul_f32 v[8:9], v[16:17], v[8:9]
	v_pk_mul_f32 v[2:3], v[10:11], v[2:3]
	v_pk_mul_f32 v[4:5], v[12:13], v[4:5]
	v_pk_add_f32 v[154:155], v[154:155], 1.0 op_sel_hi:[1,0]
	v_pk_add_f32 v[156:157], v[156:157], 1.0 op_sel_hi:[1,0]
	v_pk_add_f32 v[158:159], v[158:159], 1.0 op_sel_hi:[1,0]
	v_pk_add_f32 v[160:161], v[160:161], 1.0 op_sel_hi:[1,0]
	v_pk_mul_f32 v[6:7], v[6:7], v[138:139] op_sel_hi:[1,0]
	v_pk_mul_f32 v[8:9], v[8:9], v[138:139] op_sel_hi:[1,0]
	v_pk_mul_f32 v[2:3], v[2:3], v[138:139] op_sel_hi:[1,0]
	v_pk_mul_f32 v[4:5], v[4:5], v[138:139] op_sel_hi:[1,0]
	v_rcp_f32_e32 v154, v154
	v_rcp_f32_e32 v155, v155
	v_rcp_f32_e32 v156, v156
	v_rcp_f32_e32 v157, v157
	v_rcp_f32_e32 v158, v158
	v_rcp_f32_e32 v159, v159
	v_rcp_f32_e32 v160, v160
	v_rcp_f32_e32 v161, v161
	v_pk_mul_f32 v[6:7], v[6:7], v[154:155]
	v_pk_mul_f32 v[8:9], v[8:9], v[156:157]
	v_pk_mul_f32 v[2:3], v[2:3], v[158:159]
	v_pk_mul_f32 v[4:5], v[4:5], v[160:161]
	v_cvt_pk_bf16_f32 v14, v6, v7
	v_cvt_pk_bf16_f32 v15, v8, v9
	v_cvt_pk_bf16_f32 v16, v2, v3
	v_cvt_pk_bf16_f32 v17, v4, v5
	global_store_dwordx4 v147, v[14:17], s[36:37]
	s_andn2_b64 vcc, exec, s[2:3]
	s_mov_b64 s[2:3], -1
	s_cbranch_vccnz .LBB0_221
	s_branch .Lsw_join
